# stack14 + EpiMix bias prefetch issue point moved behind hipcc's vmcnt(0) in front of the MA K-loop (that wait no longer sits out the 4 bias loads)
# baseline (speedup 1.0000x reference)
; #define PG8_STAGE(bufoff, gbase, voff) do { _Pragma("unroll") for (int _i = 0; _i < 2; ++_i) \
;         __builtin_amdgcn_global_load_lds((const unsigned*)((const char*)(gbase) + (voff)[_i]), (PG8_LAS unsigned*)(lds + (bufoff) + ldsw + _i * 8192), 16, 0, 0); } while (0)
; #define PG8_LDA(dst, b, h) do { _Pragma("unroll") for (int m = 0; m < 4; ++m) _Pragma("unroll") for (int k = 0; k < 2; ++k) dst[m][k] = *(const PG8_LAS bf16x8*)(lds + PG8_SA(b, h) + aoff + m * 2048 + k * 1024); } while (0)
; #define PG8_WAIT_V(n) asm volatile("s_waitcnt vmcnt(" #n ")" ::: "memory")
;     __device__ __forceinline__ void operator()(const f32x4 (&acc)[2][2][4][2], const Unit& u, int wr, int wc, int fr_, int fq) const {
;     ...
;         f32x4 bv[2][2];
; #pragma unroll
;         for (int bj = 0; bj < 2; ++bj)
; #pragma unroll
;             for (int n = 0; n < 2; ++n) bv[bj][n] = *(const f32x4*)(bmg + (gate ? colt : 0) + cl + bj * HALF + 4 * n) * (gate ? 1.0f : 0.0f);
; template <class Epi, class Sched, bool ALIGN_EPI = false, bool SP2 = false, bool ABLK = false, bool BBLK = false>
; __device__ __forceinline__ void gemm_phase(PG8_LAS unsigned char* lds, const Gemm g, const Sched& S, const Epi& E) {
;     ...
;         const bool has_next = S.next(ui + 1, nxt);
;         const char* nA = has_next ? (const char*)g.A + (size_t)nxt.pm * tstepA : cA; const char* nB = has_next ? (const char*)g.Bt + (size_t)nxt.pn * tstepB : cB;
;         for (int t = 0; t < nt; t += 2) {
;             const bool last = (t == nt - 2);
;             const char* a1 = cA + (size_t)(t + 1) * kstepA;
;             const char* a2 = last ? nA : cA + (size_t)(t + 2) * kstepA; const char* b2 = last ? nB : cB + (size_t)(t + 2) * kstepB;
;             const char* a3 = a2 + kstepA; const char* b3 = b2 + kstepB;
;             if (last && has_next) S.a_ready(nxt);
;             if constexpr (SP2) {
;             PG8_LDB(B0, 0, 0); PG8_LDB(B1, 0, 1); PG8_SCHED; PG8_LDA(At, 0, 0); PG8_STAGE(PG8_SA(1, 1), a1 + hstepA, voffA);
;             PG8_WAIT_V(8); PG8_WAIT_L(0); PG8_BAR; PG8_MMA(0, 0, At, B0); PG8_MMA(0, 1, At, B1); PG8_BAR; PG8_SCHED;
;             PG8_LDA(At, 0, 1); PG8_STAGE(PG8_SB(0, 0), b2, voffB); PG8_STAGE(PG8_SB(0, 1), b2 + hstepB, voffB); PG8_STAGE(PG8_SA(0, 0), a2, voffA);
;             PG8_WAIT_V(8); PG8_WAIT_L(0); PG8_BAR; PG8_MMA(1, 0, At, B0); PG8_MMA(1, 1, At, B1); PG8_BAR; PG8_SCHED;
.LBB0_593:
	s_ashr_i32 s21, s20, 31
	s_lshl_b64 s[24:25], s[20:21], 20
	s_add_u32 s24, s51, s24
	s_addc_u32 s25, s53, s25
	s_and_b64 s[26:27], s[6:7], exec
	s_cselect_b32 s9, s25, s1
	s_cselect_b32 s16, s24, s0
	s_ashr_i32 s23, s22, 31
	s_lshl_b64 s[26:27], s[22:23], 20
	s_add_u32 s26, s44, s26
	s_addc_u32 s27, s45, s27
	s_and_b64 s[34:35], s[6:7], exec
	s_cselect_b32 s21, s27, s31
	s_cselect_b32 s23, s26, s30
	s_add_u32 s0, s0, 0xc000
	s_addc_u32 s1, s1, 0
	s_add_u32 s29, s30, 0x10000
	v_mov_b32_e32 v2, 0
	s_addc_u32 s40, s31, 0
	s_mov_b32 s41, -2
	v_mov_b32_e32 v3, v2
	v_mov_b32_e32 v4, v2
	v_mov_b32_e32 v5, v2
	v_mov_b32_e32 v6, v2
	v_mov_b32_e32 v7, v2
	v_mov_b32_e32 v8, v2
	v_mov_b32_e32 v9, v2
	s_waitcnt vmcnt(0)
	s_lshl_b32 s100, s8, 8
	s_add_i32 s100, s100, 0xfffff200
	s_cmp_gt_i32 s8, 13
	s_cselect_b32 s100, s100, 0
	s_ashr_i32 s101, s100, 31
	v_lshl_add_u64 v[250:251], s[100:101], 2, v[154:155]
	global_load_dwordx4 v[224:227], v[250:251], off
	global_load_dwordx4 v[246:249], v[250:251], off offset:16
	global_load_dwordx4 v[188:191], v[250:251], off offset:528
	s_nop 0
	global_load_dwordx4 v[250:253], v[250:251], off offset:512
	s_add_u32 s30, s0, 0x4000
	s_addc_u32 s31, s1, 0
	s_cmp_eq_u32 s41, 28
	s_cselect_b32 s36, s16, s30
	s_cselect_b32 s37, s9, s31
	s_cselect_b32 s34, s23, s29
	s_cselect_b32 s35, s21, s40
	s_add_u32 s30, s36, 0x8000
	s_addc_u32 s31, s37, 0
	s_add_i32 s60, 0, 0x10000
	s_add_i32 s75, 0, 0x14000
	v_add_u32_e32 v142, s60, v169
	v_add_u32_e32 v171, s75, v169
	ds_read_b128 v[130:133], v142
	ds_read_b128 v[134:137], v142 offset:1024
	ds_read_b128 v[138:141], v142 offset:2048
	ds_read_b128 v[142:145], v142 offset:3072
	ds_read_b128 v[160:163], v171
	ds_read_b128 v[164:167], v171 offset:1024
	ds_read_b128 v[172:175], v171 offset:2048
	ds_read_b128 v[176:179], v171 offset:3072
	v_lshl_add_u64 v[184:185], s[0:1], 0, v[156:157]
	s_add_i32 m0, s83, 0xc000
	ds_read_b128 v[180:183], v170
	ds_read_b128 v[196:199], v170 offset:1024
	ds_read_b128 v[200:203], v170 offset:2048
	ds_read_b128 v[204:207], v170 offset:3072
	ds_read_b128 v[208:211], v170 offset:4096
	ds_read_b128 v[212:215], v170 offset:5120
	ds_read_b128 v[216:219], v170 offset:6144
	ds_read_b128 v[220:223], v170 offset:7168
	global_load_lds_dwordx4 v[184:185], off
	v_lshl_add_u64 v[184:185], s[0:1], 0, v[158:159]
	s_add_i32 m0, s83, 0xe000
	s_nop 0
	global_load_lds_dwordx4 v[184:185], off
	s_waitcnt vmcnt(8)
	s_waitcnt lgkmcnt(0)
	s_barrier
	s_setprio 1
	s_waitcnt lgkmcnt(0)
	v_mfma_f32_16x16x32_bf16 v[126:129], v[130:133], v[180:183], 0
	v_mfma_f32_16x16x32_bf16 v[122:125], v[138:141], v[180:183], 0
	v_mfma_f32_16x16x32_bf16 v[110:113], v[130:133], v[200:203], 0
	v_mfma_f32_16x16x32_bf16 v[106:109], v[138:141], v[200:203], 0
	v_mfma_f32_16x16x32_bf16 v[94:97], v[130:133], v[208:211], 0
	v_mfma_f32_16x16x32_bf16 v[90:93], v[138:141], v[208:211], 0
	v_mfma_f32_16x16x32_bf16 v[78:81], v[130:133], v[216:219], 0
	v_mfma_f32_16x16x32_bf16 v[74:77], v[138:141], v[216:219], 0
	v_mfma_f32_16x16x32_bf16 v[126:129], v[134:137], v[196:199], v[126:129]
	v_mfma_f32_16x16x32_bf16 v[122:125], v[142:145], v[196:199], v[122:125]
	v_mfma_f32_16x16x32_bf16 v[110:113], v[134:137], v[204:207], v[110:113]
	v_mfma_f32_16x16x32_bf16 v[106:109], v[142:145], v[204:207], v[106:109]
	v_mfma_f32_16x16x32_bf16 v[94:97], v[134:137], v[212:215], v[94:97]
	v_mfma_f32_16x16x32_bf16 v[90:93], v[142:145], v[212:215], v[90:93]
	v_mfma_f32_16x16x32_bf16 v[78:81], v[134:137], v[220:223], v[78:81]
	v_mfma_f32_16x16x32_bf16 v[74:77], v[142:145], v[220:223], v[74:77]
	s_setprio 0
	s_setprio 1
	v_mfma_f32_16x16x32_bf16 v[118:121], v[160:163], v[180:183], 0
	v_mfma_f32_16x16x32_bf16 v[114:117], v[172:175], v[180:183], 0
	v_mfma_f32_16x16x32_bf16 v[102:105], v[160:163], v[200:203], 0
	v_mfma_f32_16x16x32_bf16 v[98:101], v[172:175], v[200:203], 0
	v_mfma_f32_16x16x32_bf16 v[86:89], v[160:163], v[208:211], 0
	v_mfma_f32_16x16x32_bf16 v[82:85], v[172:175], v[208:211], 0
	v_mfma_f32_16x16x32_bf16 v[70:73], v[160:163], v[216:219], 0
	v_mfma_f32_16x16x32_bf16 v[66:69], v[172:175], v[216:219], 0
	v_mfma_f32_16x16x32_bf16 v[118:121], v[164:167], v[196:199], v[118:121]
	v_mfma_f32_16x16x32_bf16 v[114:117], v[176:179], v[196:199], v[114:117]
	v_mfma_f32_16x16x32_bf16 v[102:105], v[164:167], v[204:207], v[102:105]
	v_mfma_f32_16x16x32_bf16 v[98:101], v[176:179], v[204:207], v[98:101]
	v_mfma_f32_16x16x32_bf16 v[86:89], v[164:167], v[212:215], v[86:89]
	v_mfma_f32_16x16x32_bf16 v[82:85], v[176:179], v[212:215], v[82:85]
	v_mfma_f32_16x16x32_bf16 v[70:73], v[164:167], v[220:223], v[70:73]
	v_mfma_f32_16x16x32_bf16 v[66:69], v[176:179], v[220:223], v[66:69]
	s_setprio 0
	s_barrier
; #define PG8_STAGE(bufoff, gbase, voff) do { _Pragma("unroll") for (int _i = 0; _i < 2; ++_i) \
;         __builtin_amdgcn_global_load_lds((const unsigned*)((const char*)(gbase) + (voff)[_i]), (PG8_LAS unsigned*)(lds + (bufoff) + ldsw + _i * 8192), 16, 0, 0); } while (0)
; #define PG8_LDA(dst, b, h) do { _Pragma("unroll") for (int m = 0; m < 4; ++m) _Pragma("unroll") for (int k = 0; k < 2; ++k) dst[m][k] = *(const PG8_LAS bf16x8*)(lds + PG8_SA(b, h) + aoff + m * 2048 + k * 1024); } while (0)
; #define PG8_MMA(ai, bj, At, Bt) do { __builtin_amdgcn_s_setprio(1); _Pragma("unroll") for (int m = 0; m < 4; ++m) _Pragma("unroll") for (int n = 0; n < 2; ++n) _Pragma("unroll") for (int k = 0; k < 2; ++k) \
;         acc[ai][bj][m][n] = __builtin_amdgcn_mfma_f32_16x16x32_bf16(Bt[n][k], At[m][k], acc[ai][bj][m][n], 0, 0, 0); __builtin_amdgcn_s_setprio(0); } while (0)
; #define PG8_WAIT_V(n) asm volatile("s_waitcnt vmcnt(" #n ")" ::: "memory")
; #define PG8_WAIT_L(n) asm volatile("s_waitcnt lgkmcnt(" #n ")" ::: "memory")
; #define PG8_BAR __builtin_amdgcn_s_barrier()
; #define PG8_SCHED __builtin_amdgcn_sched_barrier(0)
; template <class Epi, class Sched, bool ALIGN_EPI = false, bool SP2 = false, bool ABLK = false, bool BBLK = false>
; __device__ __forceinline__ void gemm_phase(PG8_LAS unsigned char* lds, const Gemm g, const Sched& S, const Epi& E) {
;     ...
;             PG8_LDA(At, 0, 1); PG8_STAGE(PG8_SB(0, 0), b2, voffB); PG8_STAGE(PG8_SB(0, 1), b2 + hstepB, voffB); PG8_STAGE(PG8_SA(0, 0), a2, voffA);
;             PG8_WAIT_V(8); PG8_WAIT_L(0); PG8_BAR; PG8_MMA(1, 0, At, B0); PG8_MMA(1, 1, At, B1); PG8_BAR; PG8_SCHED;
	s_add_i32 s60, s60, s81
	v_lshl_add_u64 v[184:185], s[34:35], 0, v[148:149]
	s_mov_b32 m0, s60
	ds_read_b128 v[180:183], v170 offset:16384
	ds_read_b128 v[196:199], v170 offset:17408
	ds_read_b128 v[200:203], v170 offset:18432
	ds_read_b128 v[204:207], v170 offset:19456
	ds_read_b128 v[208:211], v170 offset:20480
	ds_read_b128 v[212:215], v170 offset:21504
	ds_read_b128 v[216:219], v170 offset:22528
	ds_read_b128 v[220:223], v170 offset:23552
	global_load_lds_dwordx4 v[184:185], off
	s_add_i32 m0, s60, 0x2000
	s_add_u32 s60, s34, 0x4000
	v_lshl_add_u64 v[184:185], s[34:35], 0, v[152:153]
	s_addc_u32 s61, s35, 0
	s_add_i32 s75, s75, s81
	global_load_lds_dwordx4 v[184:185], off
	v_lshl_add_u64 v[184:185], s[60:61], 0, v[148:149]
	s_mov_b32 m0, s75
	s_nop 0
	global_load_lds_dwordx4 v[184:185], off
	v_lshl_add_u64 v[184:185], s[60:61], 0, v[152:153]
	s_add_i32 m0, s75, 0x2000
	s_nop 0
	global_load_lds_dwordx4 v[184:185], off
	v_lshl_add_u64 v[184:185], s[36:37], 0, v[146:147]
	s_mov_b32 m0, s83
	s_nop 0
	global_load_lds_dwordx4 v[184:185], off
	v_lshl_add_u64 v[184:185], s[36:37], 0, v[150:151]
	s_mov_b32 m0, s84
	s_nop 0
	global_load_lds_dwordx4 v[184:185], off
	s_waitcnt vmcnt(8)
	s_waitcnt lgkmcnt(0)
	s_barrier
	s_setprio 1
	s_waitcnt lgkmcnt(0)
	v_mfma_f32_16x16x32_bf16 v[62:65], v[130:133], v[180:183], 0
	v_mfma_f32_16x16x32_bf16 v[58:61], v[138:141], v[180:183], 0
	v_mfma_f32_16x16x32_bf16 v[46:49], v[130:133], v[200:203], 0
	v_mfma_f32_16x16x32_bf16 v[42:45], v[138:141], v[200:203], 0
	v_mfma_f32_16x16x32_bf16 v[30:33], v[130:133], v[208:211], 0
	v_mfma_f32_16x16x32_bf16 v[26:29], v[138:141], v[208:211], 0
	v_mfma_f32_16x16x32_bf16 v[14:17], v[130:133], v[216:219], 0
	v_mfma_f32_16x16x32_bf16 v[10:13], v[138:141], v[216:219], 0
	v_mfma_f32_16x16x32_bf16 v[62:65], v[134:137], v[196:199], v[62:65]
	v_mfma_f32_16x16x32_bf16 v[58:61], v[142:145], v[196:199], v[58:61]
	v_mfma_f32_16x16x32_bf16 v[46:49], v[134:137], v[204:207], v[46:49]
	v_mfma_f32_16x16x32_bf16 v[42:45], v[142:145], v[204:207], v[42:45]
	v_mfma_f32_16x16x32_bf16 v[30:33], v[134:137], v[212:215], v[30:33]
	v_mfma_f32_16x16x32_bf16 v[26:29], v[142:145], v[212:215], v[26:29]
	v_mfma_f32_16x16x32_bf16 v[14:17], v[134:137], v[220:223], v[14:17]
	v_mfma_f32_16x16x32_bf16 v[10:13], v[142:145], v[220:223], v[10:13]
	s_setprio 0
	s_setprio 1
	v_mfma_f32_16x16x32_bf16 v[54:57], v[160:163], v[180:183], 0
	v_mfma_f32_16x16x32_bf16 v[50:53], v[172:175], v[180:183], 0
	v_mfma_f32_16x16x32_bf16 v[38:41], v[160:163], v[200:203], 0
	v_mfma_f32_16x16x32_bf16 v[34:37], v[172:175], v[200:203], 0
	v_mfma_f32_16x16x32_bf16 v[22:25], v[160:163], v[208:211], 0
	v_mfma_f32_16x16x32_bf16 v[18:21], v[172:175], v[208:211], 0
	v_mfma_f32_16x16x32_bf16 v[6:9], v[160:163], v[216:219], 0
	v_mfma_f32_16x16x32_bf16 v[2:5], v[172:175], v[216:219], 0
	v_mfma_f32_16x16x32_bf16 v[54:57], v[164:167], v[196:199], v[54:57]
	v_mfma_f32_16x16x32_bf16 v[50:53], v[176:179], v[196:199], v[50:53]
	v_mfma_f32_16x16x32_bf16 v[38:41], v[164:167], v[204:207], v[38:41]
	v_mfma_f32_16x16x32_bf16 v[34:37], v[176:179], v[204:207], v[34:37]
	v_mfma_f32_16x16x32_bf16 v[22:25], v[164:167], v[212:215], v[22:25]
	v_mfma_f32_16x16x32_bf16 v[18:21], v[176:179], v[212:215], v[18:21]
	v_mfma_f32_16x16x32_bf16 v[6:9], v[164:167], v[220:223], v[6:9]
	v_mfma_f32_16x16x32_bf16 v[2:5], v[176:179], v[220:223], v[2:5]
	s_setprio 0
	s_barrier
	s_branch .Lmid_594
